# prologue x->bf16 loop: 2 rows of loads in flight per wave instead of 4 serialized round trips
# baseline (speedup 1.0000x reference)
.LBB0_22:
	s_add_u32 s16, s8, s1
	s_addc_u32 s17, s9, 0
	global_load_dwordx4 v[8:11], v[4:5], off offset:-2048
	global_load_dwordx4 v[12:15], v[4:5], off offset:-1024
	global_load_dwordx4 v[16:19], v[4:5], off
	global_load_dwordx4 v[20:23], v[4:5], off offset:1024
	s_add_i32 s14, s0, s20
	s_cmpk_gt_i32 s14, 0x3fff
	s_cselect_b32 s24, 0, s12
	s_cselect_b32 s25, 0, s13
	v_lshl_add_u64 v[28:29], v[4:5], 0, s[24:25]
	global_load_dwordx4 v[32:35], v[28:29], off offset:-2048
	global_load_dwordx4 v[36:39], v[28:29], off offset:-1024
	global_load_dwordx4 v[40:43], v[28:29], off
	global_load_dwordx4 v[44:47], v[28:29], off offset:1024
	s_waitcnt vmcnt(4)
.Lpro_loop:
	s_waitcnt vmcnt(9)
	v_lshl_add_u64 v[24:25], s[16:17], 0, v[2:3]
	v_cvt_pk_bf16_f32 v26, v8, v9
	v_cvt_pk_bf16_f32 v27, v10, v11
	global_store_dwordx2 v[24:25], v[26:27], off
	v_cvt_pk_bf16_f32 v48, v12, v13
	v_cvt_pk_bf16_f32 v49, v14, v15
	global_store_dwordx2 v[24:25], v[48:49], off offset:512
	v_cvt_pk_bf16_f32 v50, v16, v17
	v_cvt_pk_bf16_f32 v51, v18, v19
	global_store_dwordx2 v[24:25], v[50:51], off offset:1024
	v_cvt_pk_bf16_f32 v52, v20, v21
	v_cvt_pk_bf16_f32 v53, v22, v23
	global_store_dwordx2 v[24:25], v[52:53], off offset:1536
	v_mul_f32_e32 v7, v9, v9
	v_mul_f32_e32 v54, v11, v11
	v_fmac_f32_e32 v7, v8, v8
	v_fmac_f32_e32 v54, v10, v10
	v_add_f32_e32 v7, v7, v54
	v_mul_f32_e32 v55, v13, v13
	v_mul_f32_e32 v54, v15, v15
	v_fmac_f32_e32 v55, v12, v12
	v_fmac_f32_e32 v54, v14, v14
	v_add_f32_e32 v55, v55, v54
	v_add_f32_e32 v7, v7, v55
	v_mul_f32_e32 v55, v17, v17
	v_mul_f32_e32 v54, v19, v19
	v_fmac_f32_e32 v55, v16, v16
	v_fmac_f32_e32 v54, v18, v18
	v_add_f32_e32 v55, v55, v54
	v_add_f32_e32 v7, v7, v55
	v_mul_f32_e32 v55, v21, v21
	v_mul_f32_e32 v54, v23, v23
	v_fmac_f32_e32 v55, v20, v20
	v_fmac_f32_e32 v54, v22, v22
	v_add_f32_e32 v55, v55, v54
	v_add_f32_e32 v7, v7, v55
	ds_swizzle_b32 v55, v7 offset:swizzle(SWAP,1)
	s_waitcnt lgkmcnt(0)
	v_add_f32_e32 v7, v7, v55
	ds_swizzle_b32 v55, v7 offset:swizzle(SWAP,2)
	s_waitcnt lgkmcnt(0)
	v_add_f32_e32 v7, v7, v55
	ds_swizzle_b32 v55, v7 offset:swizzle(SWAP,4)
	s_waitcnt lgkmcnt(0)
	v_add_f32_e32 v7, v7, v55
	ds_swizzle_b32 v55, v7 offset:swizzle(SWAP,8)
	s_waitcnt lgkmcnt(0)
	v_add_f32_e32 v7, v7, v55
	ds_swizzle_b32 v55, v7 offset:swizzle(SWAP,16)
	s_waitcnt lgkmcnt(0)
	v_add_f32_e32 v7, v7, v55
	v_mov_b32_e32 v55, v7
	s_nop 1
	v_permlane32_swap_b32_e32 v7, v55
	s_and_saveexec_b64 s[14:15], s[6:7]
	v_add_f32_e32 v7, v7, v55
	v_lshl_add_u64 v[30:31], s[8:9], 0, v[0:1]
	v_cndmask_b32_e64 v7, 0, v7, s[4:5]
	global_store_dword v[30:31], v7, off
	s_or_b64 exec, exec, s[14:15]
	s_add_i32 s0, s0, s20
	v_lshl_add_u64 v[0:1], v[0:1], 0, s[10:11]
	v_lshl_add_u64 v[2:3], v[2:3], 0, s[18:19]
	s_cmpk_gt_i32 s0, 0x3fff
	s_cbranch_scc1 .Lpro_done
	s_add_i32 s14, s0, s20
	s_cmpk_gt_i32 s14, 0x3fff
	s_cselect_b32 s24, 0, s12
	s_cselect_b32 s25, 0, s13
	v_lshl_add_u64 v[4:5], v[28:29], 0, s[24:25]
	global_load_dwordx4 v[8:11], v[4:5], off offset:-2048
	global_load_dwordx4 v[12:15], v[4:5], off offset:-1024
	global_load_dwordx4 v[16:19], v[4:5], off
	global_load_dwordx4 v[20:23], v[4:5], off offset:1024
	s_waitcnt vmcnt(9)
	v_lshl_add_u64 v[24:25], s[16:17], 0, v[2:3]
	v_cvt_pk_bf16_f32 v26, v32, v33
	v_cvt_pk_bf16_f32 v27, v34, v35
	global_store_dwordx2 v[24:25], v[26:27], off
	v_cvt_pk_bf16_f32 v48, v36, v37
	v_cvt_pk_bf16_f32 v49, v38, v39
	global_store_dwordx2 v[24:25], v[48:49], off offset:512
	v_cvt_pk_bf16_f32 v50, v40, v41
	v_cvt_pk_bf16_f32 v51, v42, v43
	global_store_dwordx2 v[24:25], v[50:51], off offset:1024
	v_cvt_pk_bf16_f32 v52, v44, v45
	v_cvt_pk_bf16_f32 v53, v46, v47
	global_store_dwordx2 v[24:25], v[52:53], off offset:1536
	v_mul_f32_e32 v7, v33, v33
	v_mul_f32_e32 v54, v35, v35
	v_fmac_f32_e32 v7, v32, v32
	v_fmac_f32_e32 v54, v34, v34
	v_add_f32_e32 v7, v7, v54
	v_mul_f32_e32 v55, v37, v37
	v_mul_f32_e32 v54, v39, v39
	v_fmac_f32_e32 v55, v36, v36
	v_fmac_f32_e32 v54, v38, v38
	v_add_f32_e32 v55, v55, v54
	v_add_f32_e32 v7, v7, v55
	v_mul_f32_e32 v55, v41, v41
	v_mul_f32_e32 v54, v43, v43
	v_fmac_f32_e32 v55, v40, v40
	v_fmac_f32_e32 v54, v42, v42
	v_add_f32_e32 v55, v55, v54
	v_add_f32_e32 v7, v7, v55
	v_mul_f32_e32 v55, v45, v45
	v_mul_f32_e32 v54, v47, v47
	v_fmac_f32_e32 v55, v44, v44
	v_fmac_f32_e32 v54, v46, v46
	v_add_f32_e32 v55, v55, v54
	v_add_f32_e32 v7, v7, v55
	ds_swizzle_b32 v55, v7 offset:swizzle(SWAP,1)
	s_waitcnt lgkmcnt(0)
	v_add_f32_e32 v7, v7, v55
	ds_swizzle_b32 v55, v7 offset:swizzle(SWAP,2)
	s_waitcnt lgkmcnt(0)
	v_add_f32_e32 v7, v7, v55
	ds_swizzle_b32 v55, v7 offset:swizzle(SWAP,4)
	s_waitcnt lgkmcnt(0)
	v_add_f32_e32 v7, v7, v55
	ds_swizzle_b32 v55, v7 offset:swizzle(SWAP,8)
	s_waitcnt lgkmcnt(0)
	v_add_f32_e32 v7, v7, v55
	ds_swizzle_b32 v55, v7 offset:swizzle(SWAP,16)
	s_waitcnt lgkmcnt(0)
	v_add_f32_e32 v7, v7, v55
	v_mov_b32_e32 v55, v7
	s_nop 1
	v_permlane32_swap_b32_e32 v7, v55
	s_and_saveexec_b64 s[14:15], s[6:7]
	v_add_f32_e32 v7, v7, v55
	v_lshl_add_u64 v[30:31], s[8:9], 0, v[0:1]
	v_cndmask_b32_e64 v7, 0, v7, s[4:5]
	global_store_dword v[30:31], v7, off
	s_or_b64 exec, exec, s[14:15]
	s_add_i32 s0, s0, s20
	v_lshl_add_u64 v[0:1], v[0:1], 0, s[10:11]
	v_lshl_add_u64 v[2:3], v[2:3], 0, s[18:19]
	s_cmpk_gt_i32 s0, 0x3fff
	s_cbranch_scc1 .Lpro_done
	s_add_i32 s14, s0, s20
	s_cmpk_gt_i32 s14, 0x3fff
	s_cselect_b32 s24, 0, s12
	s_cselect_b32 s25, 0, s13
	v_lshl_add_u64 v[28:29], v[4:5], 0, s[24:25]
	global_load_dwordx4 v[32:35], v[28:29], off offset:-2048
	global_load_dwordx4 v[36:39], v[28:29], off offset:-1024
	global_load_dwordx4 v[40:43], v[28:29], off
	global_load_dwordx4 v[44:47], v[28:29], off offset:1024
	s_branch .Lpro_loop
.Lpro_done:
	s_waitcnt vmcnt(0)
.LBB0_24:
	s_load_dword s0, s[38:39], 0x90
	s_mul_i32 s23, s23, s22
	s_cmp_lt_u32 s3, 64
	v_cmp_eq_u32_e32 vcc, 0, v6
	s_movk_i32 s8, 0x8d
	s_waitcnt lgkmcnt(0)
	s_mul_i32 s23, s23, s0
	s_cselect_b64 s[0:1], -1, 0
	s_and_b64 s[58:59], s[0:1], vcc
	v_writelane_b32 v254, s18, 53
	s_cmpk_lt_i32 s2, 0x460
	s_cselect_b64 s[0:1], -1, 0
	v_writelane_b32 v254, s19, 54
	v_writelane_b32 v254, s0, 0
	s_ashr_i32 s33, s2, 31
	s_and_b32 s89, s2, 7
	v_writelane_b32 v254, s1, 1
	s_lshr_b32 s0, s33, 29
	s_add_i32 s0, s2, s0
	s_ashr_i32 s1, s0, 3
	s_and_b32 s0, s0, -8
	s_sub_i32 s0, s2, s0
	s_ashr_i32 s87, s22, 31
	s_lshl_b32 s3, s89, 6
	s_or_b32 s82, s89, 0x900
	s_cmpk_lt_i32 s2, 0x100
	s_cselect_b64 s[4:5], -1, 0
	v_writelane_b32 v254, s4, 2
	s_mov_b32 s77, 0
	s_movk_i32 s84, 0xf000
	v_writelane_b32 v254, s5, 3
	s_ashr_i32 s4, s2, 3
	s_and_b32 s4, s4, -8
	s_or_b32 s6, s4, s89
	s_bfe_u32 s5, s2, 0x30003
	s_mov_b32 s4, s6
	s_ashr_i32 s7, s6, 31
	v_writelane_b32 v254, s4, 4
	s_lshl_b64 s[6:7], s[6:7], 19
	s_movk_i32 s96, 0x81
	v_writelane_b32 v254, s5, 5
	v_writelane_b32 v254, s6, 6
	s_lshl_b32 s4, s5, 18
	s_mul_i32 s60, s20, 48
	v_writelane_b32 v254, s7, 7
	v_writelane_b32 v254, s5, 8
	v_writelane_b32 v254, s4, 9
	s_lshl_b32 s4, s0, 5
	s_cmpk_lt_i32 s2, 0x400
	s_cselect_b64 s[6:7], -1, 0
	s_lshl_b32 s5, s0, 7
	v_writelane_b32 v254, s6, 10
	s_cmpk_eq_i32 s22, 0x100
	s_mul_i32 s62, s20, 0x60
	v_writelane_b32 v254, s7, 11
	s_cselect_b64 s[6:7], -1, 0
	v_writelane_b32 v254, s6, 12
	s_cmpk_lg_i32 s22, 0x100
	s_mul_i32 s74, s20, 0x600
	v_writelane_b32 v254, s7, 13
	s_cselect_b64 s[6:7], -1, 0
	s_cmp_lt_i32 s0, 0
	v_writelane_b32 v254, s6, 14
	s_cselect_b32 s8, s8, 0x8c
	v_mov_b32_e32 v1, 0
	v_writelane_b32 v254, s7, 15
	s_mul_i32 s6, s0, 33
	s_mul_i32 s7, s0, 0x81
	s_mul_i32 s0, s0, s8
	s_cselect_b32 s4, s6, s4
	s_cselect_b32 s5, s7, s5
	s_add_i32 s0, s0, s1
	s_mul_hi_i32 s6, s0, 0xea0ea0eb
	s_add_i32 s6, s6, s0
	s_lshr_b32 s7, s6, 31
	s_ashr_i32 s6, s6, 7
	s_add_i32 s6, s6, s7
	s_mul_i32 s7, s6, 0x8c
	s_sub_i32 s7, s0, s7
	s_bfe_u32 s0, s7, 0x2001d
	s_add_i32 s8, s7, s0
	s_sext_i32_i16 s9, s8
	s_and_b32 s8, s8, 0xfffc
	s_sub_i32 s7, s7, s8
	s_lshl_b32 s6, s6, 2
	s_sext_i32_i16 s7, s7
	s_add_i32 s10, s6, s7
	s_ashr_i32 s6, s9, 2
	s_add_i32 s4, s4, s1
	v_writelane_b32 v254, s6, 16
	s_ashr_i32 s6, s4, 31
	s_lshr_b32 s6, s6, 27
	s_add_i32 s6, s4, s6
	s_ashr_i32 s7, s6, 5
	s_and_b32 s6, s6, 0xffe0
	s_sub_i32 s6, s4, s6
	s_bfe_i32 s4, s6, 0x80000
	s_bfe_u32 s4, s4, 0x3000c
	s_add_i32 s8, s6, s4
	s_bfe_i32 s4, s8, 0x80000
	s_and_b32 s8, s8, 0xf8
	s_add_i32 s1, s5, s1
	s_sub_i32 s6, s6, s8
	s_ashr_i32 s5, s1, 31
	s_lshr_b32 s0, s9, 2
	s_lshl_b32 s7, s7, 3
	s_sext_i32_i16 s9, s4
	s_sext_i32_i8 s6, s6
	s_lshr_b32 s5, s5, 25
	s_add_i32 s12, s7, s6
	s_ashr_i32 s6, s9, 3
	s_add_i32 s5, s1, s5
	v_writelane_b32 v254, s6, 17
	s_ashr_i32 s6, s5, 7
	s_and_b32 s5, s5, 0xff80
	s_sub_i32 s1, s1, s5
	s_bfe_i32 s5, s1, 0x80000
	s_bfe_u32 s5, s5, 0x3000c
	s_add_i32 s5, s1, s5
	s_lshl_b32 s7, s6, 3
	s_bfe_i32 s6, s5, 0x80000
	s_and_b32 s5, s5, 0xf8
	s_sext_i32_i16 s8, s6
	s_sub_i32 s1, s1, s5
	s_lshr_b32 s6, s8, 3
	s_sext_i32_i8 s1, s1
	s_add_i32 s14, s7, s1
	s_ashr_i32 s1, s8, 3
	s_bfe_i64 s[6:7], s[6:7], 0x100000
	v_writelane_b32 v254, s1, 18
	s_lshl_b64 s[6:7], s[6:7], 19
	v_writelane_b32 v254, s6, 19
	s_bfe_i64 s[0:1], s[0:1], 0x100000
	s_lshl_b64 s[0:1], s[0:1], 19
	v_writelane_b32 v254, s7, 20
	s_lshr_b32 s4, s9, 3
	v_writelane_b32 v254, s0, 21
	s_ashr_i32 s15, s14, 31
	s_ashr_i32 s11, s10, 31
	v_writelane_b32 v254, s1, 22
	s_bfe_i64 s[0:1], s[4:5], 0x100000
	s_lshl_b64 s[4:5], s[0:1], 19
	v_writelane_b32 v254, s4, 23
	s_lshl_b64 s[0:1], s[0:1], 21
	s_ashr_i32 s13, s12, 31
	v_writelane_b32 v254, s5, 24
	v_writelane_b32 v254, s0, 25
	s_movk_i32 s36, 0x2000
	s_movk_i32 s37, 0x4000
	v_writelane_b32 v254, s1, 26
	s_mul_i32 s0, s21, 48
	s_mul_hi_u32 s1, s20, 48
	s_add_i32 s61, s1, s0
	s_mul_i32 s0, s21, 0x60
	s_mul_hi_u32 s1, s20, 0x60
	s_add_i32 s63, s1, s0
	s_mul_i32 s0, s21, 0x600
	s_mul_hi_u32 s1, s20, 0x600
	s_add_i32 s75, s1, s0
	s_lshl_b32 s0, s3, 2
	v_writelane_b32 v254, s0, 27
	s_add_i32 s0, 0, 0x20140
	v_writelane_b32 v254, s0, 28
	s_add_i32 s0, 0, 0x20144
	v_writelane_b32 v254, s0, 29
	s_mov_b32 s0, s14
	v_writelane_b32 v254, s0, 30
	v_mov_b32_e32 v237, 0x1000
	v_mov_b32_e32 v238, 0x2000
	v_writelane_b32 v254, s1, 31
	s_lshl_b64 s[0:1], s[14:15], 19
	v_writelane_b32 v254, s0, 32
	v_mov_b32_e32 v240, 1
	v_mov_b32_e32 v241, 0x358637bd
	v_writelane_b32 v254, s1, 33
	s_mov_b32 s0, s10
	v_writelane_b32 v254, s0, 34
	v_mov_b32_e32 v242, 0x42800000
	v_mov_b32_e32 v243, 0xff800000
	v_writelane_b32 v254, s1, 35
	s_lshl_b64 s[0:1], s[10:11], 19
	v_writelane_b32 v254, s0, 36
	v_mov_b32_e32 v244, 0x41b17218
	v_mov_b64_e32 v[212:213], 0x100
	v_writelane_b32 v254, s1, 37
	s_lshl_b64 s[0:1], s[12:13], 19
	v_writelane_b32 v254, s0, 38
	s_movk_i32 s69, 0xc00
	s_mov_b32 s88, 0x3e38aa3b
	v_writelane_b32 v254, s1, 39
	s_mov_b32 s0, s12
	v_writelane_b32 v254, s0, 40
	s_mov_b32 s90, 0x800000
	s_mov_b32 s91, 0x3f317217
	v_writelane_b32 v254, s1, 41
	s_lshl_b64 s[0:1], s[12:13], 21
	v_writelane_b32 v254, s0, 42
	s_mov_b32 s30, 0x7f800000
	s_mov_b64 s[8:9], -1
	v_writelane_b32 v254, s1, 43
	s_lshl_b64 s[0:1], s[20:21], 9
	v_writelane_b32 v254, s0, 44
	s_mov_b64 s[78:79], 0x80
	s_mov_b32 s85, -1
	v_writelane_b32 v254, s1, 45
	s_mov_b64 s[0:1], 0
	v_writelane_b32 v254, s0, 46
	s_mov_b32 s86, 0xbfb8aa3b
	s_mov_b32 s28, s77
	v_writelane_b32 v254, s1, 47
	v_writelane_b32 v254, s58, 48
	s_nop 1
	v_writelane_b32 v254, s59, 49
	v_writelane_b32 v254, s82, 50
	v_writelane_b32 v254, s83, 51
	v_writelane_b32 v254, s89, 52
	s_branch .LBB0_28
